# speedup vs baseline: 1.0280x; 1.0105x over previous
; __device__ __forceinline__ unsigned pk_bf16(float lo, float hi) { f32x2 v = {lo, hi}; bf16x2_t b = __builtin_convertvector(v, bf16x2_t); return __builtin_bit_cast(unsigned, b); }
; __device__ __forceinline__ f32x4 unpack4(u32x2 w) { return (f32x4){bf_lo(w.x), bf_hi(w.x), bf_lo(w.y), bf_hi(w.y)}; }
;     __device__ __forceinline__ void operator()(const f32x4 (&acc)[2][2][4][2], const Unit& u, int wr, int wc, int fr, int fq) const {
;     ...
;         f32x4 gv[2][2];
; #pragma unroll
;         for (int bj = 0; bj < 2; ++bj)
; #pragma unroll
;             for (int n = 0; n < 2; ++n) gv[bj][n] = *(const f32x4*)(gate + (size_t)b * NMOD + c0 + bj * HALF + n * 16);
; #pragma unroll
;         for (int ai = 0; ai < 2; ++ai)
; #pragma unroll
;             for (int m = 0; m < 4; ++m) { const int rr = rowl + ai * HALF + m * 16;
; #pragma unroll
;                 for (int bj = 0; bj < 2; ++bj)
; #pragma unroll
;                     for (int n = 0; n < 2; ++n) { const int c = c0 + bj * HALF + n * 16; char* xp = (char*)xr + blk_off(rr, c, DM / 64);
;                         const f32x4 bs = base_f32 ? *(const f32x4*)(base_f32 + (size_t)rr * DM + c) : unpack4(*(const u32x2*)xp);
;                         const f32x4 o = bs + gv[bj][n] * acc[ai][bj][m][n];
;                         u32x2 w; w.x = pk_bf16(o[0], o[1]); w.y = pk_bf16(o[2], o[3]);
;                         *(u32x2*)xp = w; } }
.LBB0_697:
	s_lshl_b32 s9, s4, 8
	s_ashr_i32 s4, s4, 3
	s_add_i32 s9, s9, s77
	s_mul_hi_i32 s5, s4, 0xc000
	s_mul_i32 s4, s4, 0xc000
	v_lshl_or_b32 v162, s54, 8, v195
	s_add_u32 s4, s75, s4
	s_addc_u32 s5, s76, s5
	v_ashrrev_i32_e32 v163, 31, v162
	v_lshl_add_u64 v[56:57], v[162:163], 2, s[4:5]
	global_load_dwordx4 v[76:79], v[56:57], off
	global_load_dwordx4 v[72:75], v[56:57], off offset:64
	global_load_dwordx4 v[64:67], v[56:57], off offset:512
	s_nop 0
	global_load_dwordx4 v[56:59], v[56:57], off offset:576
	v_or_b32_e32 v166, s9, v191
	v_ashrrev_i32_e32 v167, 31, v166
	v_lshlrev_b64 v[144:145], 13, v[166:167]
	v_cndmask_b32_e64 v146, 0, 1, s[26:27]
	v_lshl_add_u64 v[144:145], s[52:53], 0, v[144:145]
	v_cmp_ne_u32_e64 s[4:5], 1, v146
	s_andn2_b64 vcc, exec, s[26:27]
	v_lshl_add_u64 v[178:179], v[162:163], 2, v[144:145]
	s_cbranch_vccnz .LBB0_699
	global_load_dwordx4 v[202:205], v[178:179], off
	global_load_dwordx4 v[206:209], v[178:179], off offset:64
	global_load_dwordx4 v[218:221], v[178:179], off offset:512
	global_load_dwordx4 v[232:235], v[178:179], off offset:576
	s_waitcnt vmcnt(0)
	v_mov_b32_e32 v144, v202
	v_mov_b32_e32 v145, v203
	v_mov_b32_e32 v146, v204
	v_mov_b32_e32 v147, v205
	s_mov_b64 s[58:59], 0
	s_branch .LBB0_700

; __device__ __forceinline__ unsigned pk_bf16(float lo, float hi) { f32x2 v = {lo, hi}; bf16x2_t b = __builtin_convertvector(v, bf16x2_t); return __builtin_bit_cast(unsigned, b); }
; __device__ __forceinline__ f32x4 unpack4(u32x2 w) { return (f32x4){bf_lo(w.x), bf_hi(w.x), bf_lo(w.y), bf_hi(w.y)}; }
;     __device__ __forceinline__ void operator()(const f32x4 (&acc)[2][2][4][2], const Unit& u, int wr, int wc, int fr, int fq) const {
;     ...
;             for (int m = 0; m < 4; ++m) { const int rr = rowl + ai * HALF + m * 16;
; #pragma unroll
;                 for (int bj = 0; bj < 2; ++bj)
; #pragma unroll
;                     for (int n = 0; n < 2; ++n) { const int c = c0 + bj * HALF + n * 16; char* xp = (char*)xr + blk_off(rr, c, DM / 64);
;                         const f32x4 bs = base_f32 ? *(const f32x4*)(base_f32 + (size_t)rr * DM + c) : unpack4(*(const u32x2*)xp);
;                         const f32x4 o = bs + gv[bj][n] * acc[ai][bj][m][n];
;                         u32x2 w; w.x = pk_bf16(o[0], o[1]); w.y = pk_bf16(o[2], o[3]);
;                         *(u32x2*)xp = w; } }
.LBB0_702:
	s_waitcnt vmcnt(3)
	v_pk_fma_f32 v[142:143], v[142:143], v[78:79], v[146:147]
	v_pk_fma_f32 v[140:141], v[140:141], v[76:77], v[144:145]
	s_and_b64 vcc, exec, s[4:5]
	v_cvt_pk_bf16_f32 v140, v140, v141
	v_cvt_pk_bf16_f32 v141, v142, v143
	global_store_dwordx2 v[176:177], v[140:141], off
	s_cbranch_vccnz .LBB0_704
	v_mov_b32_e32 v140, v206
	v_mov_b32_e32 v141, v207
	v_mov_b32_e32 v142, v208
	v_mov_b32_e32 v143, v209
	s_mov_b64 s[58:59], 0
	s_branch .LBB0_705

; __device__ __forceinline__ unsigned pk_bf16(float lo, float hi) { f32x2 v = {lo, hi}; bf16x2_t b = __builtin_convertvector(v, bf16x2_t); return __builtin_bit_cast(unsigned, b); }
; __device__ __forceinline__ f32x4 unpack4(u32x2 w) { return (f32x4){bf_lo(w.x), bf_hi(w.x), bf_lo(w.y), bf_hi(w.y)}; }
;     __device__ __forceinline__ void operator()(const f32x4 (&acc)[2][2][4][2], const Unit& u, int wr, int wc, int fr, int fq) const {
;     ...
;             for (int m = 0; m < 4; ++m) { const int rr = rowl + ai * HALF + m * 16;
; #pragma unroll
;                 for (int bj = 0; bj < 2; ++bj)
; #pragma unroll
;                     for (int n = 0; n < 2; ++n) { const int c = c0 + bj * HALF + n * 16; char* xp = (char*)xr + blk_off(rr, c, DM / 64);
;                         const f32x4 bs = base_f32 ? *(const f32x4*)(base_f32 + (size_t)rr * DM + c) : unpack4(*(const u32x2*)xp);
;                         const f32x4 o = bs + gv[bj][n] * acc[ai][bj][m][n];
;                         u32x2 w; w.x = pk_bf16(o[0], o[1]); w.y = pk_bf16(o[2], o[3]);
;                         *(u32x2*)xp = w; } }
.LBB0_707:
	s_waitcnt vmcnt(3)
	v_pk_fma_f32 v[138:139], v[138:139], v[74:75], v[142:143]
	v_pk_fma_f32 v[136:137], v[136:137], v[72:73], v[140:141]
	s_and_b64 vcc, exec, s[4:5]
	v_cvt_pk_bf16_f32 v136, v136, v137
	v_cvt_pk_bf16_f32 v137, v138, v139
	global_store_dwordx2 v[174:175], v[136:137], off
	s_cbranch_vccnz .LBB0_709
	v_mov_b32_e32 v136, v218
	v_mov_b32_e32 v137, v219
	v_mov_b32_e32 v138, v220
	v_mov_b32_e32 v139, v221
	s_mov_b64 s[58:59], 0
	s_branch .LBB0_710

; __device__ __forceinline__ unsigned pk_bf16(float lo, float hi) { f32x2 v = {lo, hi}; bf16x2_t b = __builtin_convertvector(v, bf16x2_t); return __builtin_bit_cast(unsigned, b); }
; __device__ __forceinline__ f32x4 unpack4(u32x2 w) { return (f32x4){bf_lo(w.x), bf_hi(w.x), bf_lo(w.y), bf_hi(w.y)}; }
;     __device__ __forceinline__ void operator()(const f32x4 (&acc)[2][2][4][2], const Unit& u, int wr, int wc, int fr, int fq) const {
;     ...
;             for (int m = 0; m < 4; ++m) { const int rr = rowl + ai * HALF + m * 16;
; #pragma unroll
;                 for (int bj = 0; bj < 2; ++bj)
; #pragma unroll
;                     for (int n = 0; n < 2; ++n) { const int c = c0 + bj * HALF + n * 16; char* xp = (char*)xr + blk_off(rr, c, DM / 64);
;                         const f32x4 bs = base_f32 ? *(const f32x4*)(base_f32 + (size_t)rr * DM + c) : unpack4(*(const u32x2*)xp);
;                         const f32x4 o = bs + gv[bj][n] * acc[ai][bj][m][n];
;                         u32x2 w; w.x = pk_bf16(o[0], o[1]); w.y = pk_bf16(o[2], o[3]);
;                         *(u32x2*)xp = w; } }
.LBB0_712:
	s_waitcnt vmcnt(3)
	v_pk_fma_f32 v[134:135], v[134:135], v[66:67], v[138:139]
	v_pk_fma_f32 v[132:133], v[132:133], v[64:65], v[136:137]
	s_and_b64 vcc, exec, s[4:5]
	v_cvt_pk_bf16_f32 v132, v132, v133
	v_cvt_pk_bf16_f32 v133, v134, v135
	global_store_dwordx2 v[180:181], v[132:133], off
	s_cbranch_vccnz .LBB0_714
	v_mov_b32_e32 v132, v232
	v_mov_b32_e32 v133, v233
	v_mov_b32_e32 v134, v234
	v_mov_b32_e32 v135, v235
	s_mov_b64 s[58:59], 0
	s_branch .LBB0_715

; __device__ __forceinline__ unsigned pk_bf16(float lo, float hi) { f32x2 v = {lo, hi}; bf16x2_t b = __builtin_convertvector(v, bf16x2_t); return __builtin_bit_cast(unsigned, b); }
; __device__ __forceinline__ f32x4 unpack4(u32x2 w) { return (f32x4){bf_lo(w.x), bf_hi(w.x), bf_lo(w.y), bf_hi(w.y)}; }
;     __device__ __forceinline__ void operator()(const f32x4 (&acc)[2][2][4][2], const Unit& u, int wr, int wc, int fr, int fq) const {
;     ...
;             for (int m = 0; m < 4; ++m) { const int rr = rowl + ai * HALF + m * 16;
; #pragma unroll
;                 for (int bj = 0; bj < 2; ++bj)
; #pragma unroll
;                     for (int n = 0; n < 2; ++n) { const int c = c0 + bj * HALF + n * 16; char* xp = (char*)xr + blk_off(rr, c, DM / 64);
;                         const f32x4 bs = base_f32 ? *(const f32x4*)(base_f32 + (size_t)rr * DM + c) : unpack4(*(const u32x2*)xp);
;                         const f32x4 o = bs + gv[bj][n] * acc[ai][bj][m][n];
;                         u32x2 w; w.x = pk_bf16(o[0], o[1]); w.y = pk_bf16(o[2], o[3]);
;                         *(u32x2*)xp = w; } }
.LBB0_717:
	s_waitcnt vmcnt(3)
	v_pk_fma_f32 v[130:131], v[130:131], v[58:59], v[134:135]
	v_pk_fma_f32 v[128:129], v[128:129], v[56:57], v[132:133]
	v_or_b32_e32 v134, 16, v166
	v_cvt_pk_bf16_f32 v128, v128, v129
	v_cvt_pk_bf16_f32 v129, v130, v131
	v_ashrrev_i32_e32 v135, 31, v134
	global_store_dwordx2 v[182:183], v[128:129], off
	v_lshlrev_b64 v[128:129], 13, v[134:135]
	v_lshl_add_u64 v[128:129], s[52:53], 0, v[128:129]
	s_and_b64 vcc, exec, s[4:5]
	v_lshl_add_u64 v[132:133], v[162:163], 2, v[128:129]
	s_cbranch_vccnz .LBB0_719
	global_load_dwordx4 v[202:205], v[132:133], off
	global_load_dwordx4 v[206:209], v[132:133], off offset:64
	global_load_dwordx4 v[218:221], v[132:133], off offset:512
	global_load_dwordx4 v[232:235], v[132:133], off offset:576
	s_waitcnt vmcnt(0)
	v_mov_b32_e32 v128, v202
	v_mov_b32_e32 v129, v203
	v_mov_b32_e32 v130, v204
	v_mov_b32_e32 v131, v205
	s_mov_b64 s[54:55], 0
	s_branch .LBB0_720

; __device__ __forceinline__ unsigned pk_bf16(float lo, float hi) { f32x2 v = {lo, hi}; bf16x2_t b = __builtin_convertvector(v, bf16x2_t); return __builtin_bit_cast(unsigned, b); }
; __device__ __forceinline__ f32x4 unpack4(u32x2 w) { return (f32x4){bf_lo(w.x), bf_hi(w.x), bf_lo(w.y), bf_hi(w.y)}; }
;     __device__ __forceinline__ void operator()(const f32x4 (&acc)[2][2][4][2], const Unit& u, int wr, int wc, int fr, int fq) const {
;     ...
;             for (int m = 0; m < 4; ++m) { const int rr = rowl + ai * HALF + m * 16;
; #pragma unroll
;                 for (int bj = 0; bj < 2; ++bj)
; #pragma unroll
;                     for (int n = 0; n < 2; ++n) { const int c = c0 + bj * HALF + n * 16; char* xp = (char*)xr + blk_off(rr, c, DM / 64);
;                         const f32x4 bs = base_f32 ? *(const f32x4*)(base_f32 + (size_t)rr * DM + c) : unpack4(*(const u32x2*)xp);
;                         const f32x4 o = bs + gv[bj][n] * acc[ai][bj][m][n];
;                         u32x2 w; w.x = pk_bf16(o[0], o[1]); w.y = pk_bf16(o[2], o[3]);
;                         *(u32x2*)xp = w; } }
.LBB0_722:
	s_waitcnt vmcnt(3)
	v_pk_fma_f32 v[126:127], v[126:127], v[78:79], v[130:131]
	v_pk_fma_f32 v[124:125], v[124:125], v[76:77], v[128:129]
	s_and_b64 vcc, exec, s[4:5]
	v_cvt_pk_bf16_f32 v124, v124, v125
	v_cvt_pk_bf16_f32 v125, v126, v127
	global_store_dwordx2 v[184:185], v[124:125], off
	s_cbranch_vccnz .LBB0_724
	v_mov_b32_e32 v124, v206
	v_mov_b32_e32 v125, v207
	v_mov_b32_e32 v126, v208
	v_mov_b32_e32 v127, v209
	s_mov_b64 s[54:55], 0
	s_branch .LBB0_725

; __device__ __forceinline__ unsigned pk_bf16(float lo, float hi) { f32x2 v = {lo, hi}; bf16x2_t b = __builtin_convertvector(v, bf16x2_t); return __builtin_bit_cast(unsigned, b); }
; __device__ __forceinline__ f32x4 unpack4(u32x2 w) { return (f32x4){bf_lo(w.x), bf_hi(w.x), bf_lo(w.y), bf_hi(w.y)}; }
;     __device__ __forceinline__ void operator()(const f32x4 (&acc)[2][2][4][2], const Unit& u, int wr, int wc, int fr, int fq) const {
;     ...
;             for (int m = 0; m < 4; ++m) { const int rr = rowl + ai * HALF + m * 16;
; #pragma unroll
;                 for (int bj = 0; bj < 2; ++bj)
; #pragma unroll
;                     for (int n = 0; n < 2; ++n) { const int c = c0 + bj * HALF + n * 16; char* xp = (char*)xr + blk_off(rr, c, DM / 64);
;                         const f32x4 bs = base_f32 ? *(const f32x4*)(base_f32 + (size_t)rr * DM + c) : unpack4(*(const u32x2*)xp);
;                         const f32x4 o = bs + gv[bj][n] * acc[ai][bj][m][n];
;                         u32x2 w; w.x = pk_bf16(o[0], o[1]); w.y = pk_bf16(o[2], o[3]);
;                         *(u32x2*)xp = w; } }
.LBB0_727:
	s_waitcnt vmcnt(3)
	v_pk_fma_f32 v[122:123], v[122:123], v[74:75], v[126:127]
	v_pk_fma_f32 v[120:121], v[120:121], v[72:73], v[124:125]
	s_and_b64 vcc, exec, s[4:5]
	v_cvt_pk_bf16_f32 v120, v120, v121
	v_cvt_pk_bf16_f32 v121, v122, v123
	global_store_dwordx2 v[128:129], v[120:121], off
	s_cbranch_vccnz .LBB0_729
	v_mov_b32_e32 v120, v218
	v_mov_b32_e32 v121, v219
	v_mov_b32_e32 v122, v220
	v_mov_b32_e32 v123, v221
	s_mov_b64 s[54:55], 0
	s_branch .LBB0_730

; __device__ __forceinline__ unsigned pk_bf16(float lo, float hi) { f32x2 v = {lo, hi}; bf16x2_t b = __builtin_convertvector(v, bf16x2_t); return __builtin_bit_cast(unsigned, b); }
; __device__ __forceinline__ f32x4 unpack4(u32x2 w) { return (f32x4){bf_lo(w.x), bf_hi(w.x), bf_lo(w.y), bf_hi(w.y)}; }
;     __device__ __forceinline__ void operator()(const f32x4 (&acc)[2][2][4][2], const Unit& u, int wr, int wc, int fr, int fq) const {
;     ...
;             for (int m = 0; m < 4; ++m) { const int rr = rowl + ai * HALF + m * 16;
; #pragma unroll
;                 for (int bj = 0; bj < 2; ++bj)
; #pragma unroll
;                     for (int n = 0; n < 2; ++n) { const int c = c0 + bj * HALF + n * 16; char* xp = (char*)xr + blk_off(rr, c, DM / 64);
;                         const f32x4 bs = base_f32 ? *(const f32x4*)(base_f32 + (size_t)rr * DM + c) : unpack4(*(const u32x2*)xp);
;                         const f32x4 o = bs + gv[bj][n] * acc[ai][bj][m][n];
;                         u32x2 w; w.x = pk_bf16(o[0], o[1]); w.y = pk_bf16(o[2], o[3]);
;                         *(u32x2*)xp = w; } }
.LBB0_732:
	s_waitcnt vmcnt(3)
	v_pk_fma_f32 v[118:119], v[118:119], v[66:67], v[122:123]
	v_pk_fma_f32 v[116:117], v[116:117], v[64:65], v[120:121]
	s_and_b64 vcc, exec, s[4:5]
	v_cvt_pk_bf16_f32 v116, v116, v117
	v_cvt_pk_bf16_f32 v117, v118, v119
	global_store_dwordx2 v[124:125], v[116:117], off
	s_cbranch_vccnz .LBB0_734
	v_mov_b32_e32 v116, v232
	v_mov_b32_e32 v117, v233
	v_mov_b32_e32 v118, v234
	v_mov_b32_e32 v119, v235
	s_mov_b64 s[54:55], 0
	s_branch .LBB0_735

; __device__ __forceinline__ unsigned pk_bf16(float lo, float hi) { f32x2 v = {lo, hi}; bf16x2_t b = __builtin_convertvector(v, bf16x2_t); return __builtin_bit_cast(unsigned, b); }
; __device__ __forceinline__ f32x4 unpack4(u32x2 w) { return (f32x4){bf_lo(w.x), bf_hi(w.x), bf_lo(w.y), bf_hi(w.y)}; }
;     __device__ __forceinline__ void operator()(const f32x4 (&acc)[2][2][4][2], const Unit& u, int wr, int wc, int fr, int fq) const {
;     ...
;             for (int m = 0; m < 4; ++m) { const int rr = rowl + ai * HALF + m * 16;
; #pragma unroll
;                 for (int bj = 0; bj < 2; ++bj)
; #pragma unroll
;                     for (int n = 0; n < 2; ++n) { const int c = c0 + bj * HALF + n * 16; char* xp = (char*)xr + blk_off(rr, c, DM / 64);
;                         const f32x4 bs = base_f32 ? *(const f32x4*)(base_f32 + (size_t)rr * DM + c) : unpack4(*(const u32x2*)xp);
;                         const f32x4 o = bs + gv[bj][n] * acc[ai][bj][m][n];
;                         u32x2 w; w.x = pk_bf16(o[0], o[1]); w.y = pk_bf16(o[2], o[3]);
;                         *(u32x2*)xp = w; } }
.LBB0_737:
	s_waitcnt vmcnt(3)
	v_pk_fma_f32 v[114:115], v[114:115], v[58:59], v[118:119]
	v_pk_fma_f32 v[112:113], v[112:113], v[56:57], v[116:117]
	v_or_b32_e32 v118, 32, v166
	v_cvt_pk_bf16_f32 v112, v112, v113
	v_cvt_pk_bf16_f32 v113, v114, v115
	v_ashrrev_i32_e32 v119, 31, v118
	global_store_dwordx2 v[120:121], v[112:113], off
	v_lshlrev_b64 v[112:113], 13, v[118:119]
	v_lshl_add_u64 v[112:113], s[52:53], 0, v[112:113]
	s_and_b64 vcc, exec, s[4:5]
	v_lshl_add_u64 v[116:117], v[162:163], 2, v[112:113]
	s_cbranch_vccnz .LBB0_739
	global_load_dwordx4 v[202:205], v[116:117], off
	global_load_dwordx4 v[206:209], v[116:117], off offset:64
	global_load_dwordx4 v[218:221], v[116:117], off offset:512
	global_load_dwordx4 v[232:235], v[116:117], off offset:576
	s_waitcnt vmcnt(0)
	v_mov_b32_e32 v112, v202
	v_mov_b32_e32 v113, v203
	v_mov_b32_e32 v114, v204
	v_mov_b32_e32 v115, v205
	s_mov_b64 s[54:55], 0
	s_branch .LBB0_740

; __device__ __forceinline__ unsigned pk_bf16(float lo, float hi) { f32x2 v = {lo, hi}; bf16x2_t b = __builtin_convertvector(v, bf16x2_t); return __builtin_bit_cast(unsigned, b); }
; __device__ __forceinline__ f32x4 unpack4(u32x2 w) { return (f32x4){bf_lo(w.x), bf_hi(w.x), bf_lo(w.y), bf_hi(w.y)}; }
;     __device__ __forceinline__ void operator()(const f32x4 (&acc)[2][2][4][2], const Unit& u, int wr, int wc, int fr, int fq) const {
;     ...
;             for (int m = 0; m < 4; ++m) { const int rr = rowl + ai * HALF + m * 16;
; #pragma unroll
;                 for (int bj = 0; bj < 2; ++bj)
; #pragma unroll
;                     for (int n = 0; n < 2; ++n) { const int c = c0 + bj * HALF + n * 16; char* xp = (char*)xr + blk_off(rr, c, DM / 64);
;                         const f32x4 bs = base_f32 ? *(const f32x4*)(base_f32 + (size_t)rr * DM + c) : unpack4(*(const u32x2*)xp);
;                         const f32x4 o = bs + gv[bj][n] * acc[ai][bj][m][n];
;                         u32x2 w; w.x = pk_bf16(o[0], o[1]); w.y = pk_bf16(o[2], o[3]);
;                         *(u32x2*)xp = w; } }
.LBB0_742:
	s_waitcnt vmcnt(3)
	v_pk_fma_f32 v[110:111], v[110:111], v[78:79], v[114:115]
	v_pk_fma_f32 v[108:109], v[108:109], v[76:77], v[112:113]
	s_and_b64 vcc, exec, s[4:5]
	v_cvt_pk_bf16_f32 v108, v108, v109
	v_cvt_pk_bf16_f32 v109, v110, v111
	global_store_dwordx2 v[122:123], v[108:109], off
	s_cbranch_vccnz .LBB0_744
	v_mov_b32_e32 v108, v206
	v_mov_b32_e32 v109, v207
	v_mov_b32_e32 v110, v208
	v_mov_b32_e32 v111, v209
	s_mov_b64 s[54:55], 0
	s_branch .LBB0_745

; __device__ __forceinline__ unsigned pk_bf16(float lo, float hi) { f32x2 v = {lo, hi}; bf16x2_t b = __builtin_convertvector(v, bf16x2_t); return __builtin_bit_cast(unsigned, b); }
; __device__ __forceinline__ f32x4 unpack4(u32x2 w) { return (f32x4){bf_lo(w.x), bf_hi(w.x), bf_lo(w.y), bf_hi(w.y)}; }
;     __device__ __forceinline__ void operator()(const f32x4 (&acc)[2][2][4][2], const Unit& u, int wr, int wc, int fr, int fq) const {
;     ...
;             for (int m = 0; m < 4; ++m) { const int rr = rowl + ai * HALF + m * 16;
; #pragma unroll
;                 for (int bj = 0; bj < 2; ++bj)
; #pragma unroll
;                     for (int n = 0; n < 2; ++n) { const int c = c0 + bj * HALF + n * 16; char* xp = (char*)xr + blk_off(rr, c, DM / 64);
;                         const f32x4 bs = base_f32 ? *(const f32x4*)(base_f32 + (size_t)rr * DM + c) : unpack4(*(const u32x2*)xp);
;                         const f32x4 o = bs + gv[bj][n] * acc[ai][bj][m][n];
;                         u32x2 w; w.x = pk_bf16(o[0], o[1]); w.y = pk_bf16(o[2], o[3]);
;                         *(u32x2*)xp = w; } }
.LBB0_747:
	s_waitcnt vmcnt(3)
	v_pk_fma_f32 v[106:107], v[106:107], v[74:75], v[110:111]
	v_pk_fma_f32 v[104:105], v[104:105], v[72:73], v[108:109]
	s_and_b64 vcc, exec, s[4:5]
	v_cvt_pk_bf16_f32 v104, v104, v105
	v_cvt_pk_bf16_f32 v105, v106, v107
	global_store_dwordx2 v[112:113], v[104:105], off
	s_cbranch_vccnz .LBB0_749
	v_mov_b32_e32 v104, v218
	v_mov_b32_e32 v105, v219
	v_mov_b32_e32 v106, v220
	v_mov_b32_e32 v107, v221
	s_mov_b64 s[54:55], 0
	s_branch .LBB0_750

; __device__ __forceinline__ unsigned pk_bf16(float lo, float hi) { f32x2 v = {lo, hi}; bf16x2_t b = __builtin_convertvector(v, bf16x2_t); return __builtin_bit_cast(unsigned, b); }
; __device__ __forceinline__ f32x4 unpack4(u32x2 w) { return (f32x4){bf_lo(w.x), bf_hi(w.x), bf_lo(w.y), bf_hi(w.y)}; }
;     __device__ __forceinline__ void operator()(const f32x4 (&acc)[2][2][4][2], const Unit& u, int wr, int wc, int fr, int fq) const {
;     ...
;             for (int m = 0; m < 4; ++m) { const int rr = rowl + ai * HALF + m * 16;
; #pragma unroll
;                 for (int bj = 0; bj < 2; ++bj)
; #pragma unroll
;                     for (int n = 0; n < 2; ++n) { const int c = c0 + bj * HALF + n * 16; char* xp = (char*)xr + blk_off(rr, c, DM / 64);
;                         const f32x4 bs = base_f32 ? *(const f32x4*)(base_f32 + (size_t)rr * DM + c) : unpack4(*(const u32x2*)xp);
;                         const f32x4 o = bs + gv[bj][n] * acc[ai][bj][m][n];
;                         u32x2 w; w.x = pk_bf16(o[0], o[1]); w.y = pk_bf16(o[2], o[3]);
;                         *(u32x2*)xp = w; } }
.LBB0_752:
	s_waitcnt vmcnt(3)
	v_pk_fma_f32 v[102:103], v[102:103], v[66:67], v[106:107]
	v_pk_fma_f32 v[100:101], v[100:101], v[64:65], v[104:105]
	s_and_b64 vcc, exec, s[4:5]
	v_cvt_pk_bf16_f32 v100, v100, v101
	v_cvt_pk_bf16_f32 v101, v102, v103
	global_store_dwordx2 v[108:109], v[100:101], off
	s_cbranch_vccnz .LBB0_754
	v_mov_b32_e32 v100, v232
	v_mov_b32_e32 v101, v233
	v_mov_b32_e32 v102, v234
	v_mov_b32_e32 v103, v235
	s_mov_b64 s[54:55], 0
	s_branch .LBB0_755

; __device__ __forceinline__ unsigned pk_bf16(float lo, float hi) { f32x2 v = {lo, hi}; bf16x2_t b = __builtin_convertvector(v, bf16x2_t); return __builtin_bit_cast(unsigned, b); }
; __device__ __forceinline__ f32x4 unpack4(u32x2 w) { return (f32x4){bf_lo(w.x), bf_hi(w.x), bf_lo(w.y), bf_hi(w.y)}; }
;     __device__ __forceinline__ void operator()(const f32x4 (&acc)[2][2][4][2], const Unit& u, int wr, int wc, int fr, int fq) const {
;     ...
;             for (int m = 0; m < 4; ++m) { const int rr = rowl + ai * HALF + m * 16;
; #pragma unroll
;                 for (int bj = 0; bj < 2; ++bj)
; #pragma unroll
;                     for (int n = 0; n < 2; ++n) { const int c = c0 + bj * HALF + n * 16; char* xp = (char*)xr + blk_off(rr, c, DM / 64);
;                         const f32x4 bs = base_f32 ? *(const f32x4*)(base_f32 + (size_t)rr * DM + c) : unpack4(*(const u32x2*)xp);
;                         const f32x4 o = bs + gv[bj][n] * acc[ai][bj][m][n];
;                         u32x2 w; w.x = pk_bf16(o[0], o[1]); w.y = pk_bf16(o[2], o[3]);
;                         *(u32x2*)xp = w; } }
.LBB0_757:
	s_waitcnt vmcnt(3)
	v_pk_fma_f32 v[98:99], v[98:99], v[58:59], v[102:103]
	v_pk_fma_f32 v[96:97], v[96:97], v[56:57], v[100:101]
	v_or_b32_e32 v102, 48, v166
	v_cvt_pk_bf16_f32 v96, v96, v97
	v_cvt_pk_bf16_f32 v97, v98, v99
	v_ashrrev_i32_e32 v103, 31, v102
	global_store_dwordx2 v[104:105], v[96:97], off
	v_lshlrev_b64 v[96:97], 13, v[102:103]
	v_lshl_add_u64 v[96:97], s[52:53], 0, v[96:97]
	s_and_b64 vcc, exec, s[4:5]
	v_lshl_add_u64 v[100:101], v[162:163], 2, v[96:97]
	s_cbranch_vccnz .LBB0_759
	global_load_dwordx4 v[202:205], v[100:101], off
	global_load_dwordx4 v[206:209], v[100:101], off offset:64
	global_load_dwordx4 v[218:221], v[100:101], off offset:512
	global_load_dwordx4 v[232:235], v[100:101], off offset:576
	s_waitcnt vmcnt(0)
	v_mov_b32_e32 v96, v202
	v_mov_b32_e32 v97, v203
	v_mov_b32_e32 v98, v204
	v_mov_b32_e32 v99, v205
	s_mov_b64 s[54:55], 0
	s_branch .LBB0_760

; __device__ __forceinline__ unsigned pk_bf16(float lo, float hi) { f32x2 v = {lo, hi}; bf16x2_t b = __builtin_convertvector(v, bf16x2_t); return __builtin_bit_cast(unsigned, b); }
; __device__ __forceinline__ f32x4 unpack4(u32x2 w) { return (f32x4){bf_lo(w.x), bf_hi(w.x), bf_lo(w.y), bf_hi(w.y)}; }
;     __device__ __forceinline__ void operator()(const f32x4 (&acc)[2][2][4][2], const Unit& u, int wr, int wc, int fr, int fq) const {
;     ...
;             for (int m = 0; m < 4; ++m) { const int rr = rowl + ai * HALF + m * 16;
; #pragma unroll
;                 for (int bj = 0; bj < 2; ++bj)
; #pragma unroll
;                     for (int n = 0; n < 2; ++n) { const int c = c0 + bj * HALF + n * 16; char* xp = (char*)xr + blk_off(rr, c, DM / 64);
;                         const f32x4 bs = base_f32 ? *(const f32x4*)(base_f32 + (size_t)rr * DM + c) : unpack4(*(const u32x2*)xp);
;                         const f32x4 o = bs + gv[bj][n] * acc[ai][bj][m][n];
;                         u32x2 w; w.x = pk_bf16(o[0], o[1]); w.y = pk_bf16(o[2], o[3]);
;                         *(u32x2*)xp = w; } }
.LBB0_762:
	s_waitcnt vmcnt(3)
	v_pk_fma_f32 v[94:95], v[94:95], v[78:79], v[98:99]
	v_pk_fma_f32 v[92:93], v[92:93], v[76:77], v[96:97]
	s_and_b64 vcc, exec, s[4:5]
	v_cvt_pk_bf16_f32 v92, v92, v93
	v_cvt_pk_bf16_f32 v93, v94, v95
	global_store_dwordx2 v[106:107], v[92:93], off
	s_cbranch_vccnz .LBB0_764
	v_mov_b32_e32 v92, v206
	v_mov_b32_e32 v93, v207
	v_mov_b32_e32 v94, v208
	v_mov_b32_e32 v95, v209
	s_mov_b64 s[54:55], 0
	s_branch .LBB0_765

; __device__ __forceinline__ unsigned pk_bf16(float lo, float hi) { f32x2 v = {lo, hi}; bf16x2_t b = __builtin_convertvector(v, bf16x2_t); return __builtin_bit_cast(unsigned, b); }
; __device__ __forceinline__ f32x4 unpack4(u32x2 w) { return (f32x4){bf_lo(w.x), bf_hi(w.x), bf_lo(w.y), bf_hi(w.y)}; }
;     __device__ __forceinline__ void operator()(const f32x4 (&acc)[2][2][4][2], const Unit& u, int wr, int wc, int fr, int fq) const {
;     ...
;             for (int m = 0; m < 4; ++m) { const int rr = rowl + ai * HALF + m * 16;
; #pragma unroll
;                 for (int bj = 0; bj < 2; ++bj)
; #pragma unroll
;                     for (int n = 0; n < 2; ++n) { const int c = c0 + bj * HALF + n * 16; char* xp = (char*)xr + blk_off(rr, c, DM / 64);
;                         const f32x4 bs = base_f32 ? *(const f32x4*)(base_f32 + (size_t)rr * DM + c) : unpack4(*(const u32x2*)xp);
;                         const f32x4 o = bs + gv[bj][n] * acc[ai][bj][m][n];
;                         u32x2 w; w.x = pk_bf16(o[0], o[1]); w.y = pk_bf16(o[2], o[3]);
;                         *(u32x2*)xp = w; } }
.LBB0_767:
	s_waitcnt vmcnt(3)
	v_pk_fma_f32 v[90:91], v[90:91], v[74:75], v[94:95]
	v_pk_fma_f32 v[88:89], v[88:89], v[72:73], v[92:93]
	s_and_b64 vcc, exec, s[4:5]
	v_cvt_pk_bf16_f32 v88, v88, v89
	v_cvt_pk_bf16_f32 v89, v90, v91
	global_store_dwordx2 v[96:97], v[88:89], off
	s_cbranch_vccnz .LBB0_769
	v_mov_b32_e32 v88, v218
	v_mov_b32_e32 v89, v219
	v_mov_b32_e32 v90, v220
	v_mov_b32_e32 v91, v221
	s_mov_b64 s[54:55], 0
	s_branch .LBB0_770

; __device__ __forceinline__ unsigned pk_bf16(float lo, float hi) { f32x2 v = {lo, hi}; bf16x2_t b = __builtin_convertvector(v, bf16x2_t); return __builtin_bit_cast(unsigned, b); }
; __device__ __forceinline__ f32x4 unpack4(u32x2 w) { return (f32x4){bf_lo(w.x), bf_hi(w.x), bf_lo(w.y), bf_hi(w.y)}; }
;     __device__ __forceinline__ void operator()(const f32x4 (&acc)[2][2][4][2], const Unit& u, int wr, int wc, int fr, int fq) const {
;     ...
;             for (int m = 0; m < 4; ++m) { const int rr = rowl + ai * HALF + m * 16;
; #pragma unroll
;                 for (int bj = 0; bj < 2; ++bj)
; #pragma unroll
;                     for (int n = 0; n < 2; ++n) { const int c = c0 + bj * HALF + n * 16; char* xp = (char*)xr + blk_off(rr, c, DM / 64);
;                         const f32x4 bs = base_f32 ? *(const f32x4*)(base_f32 + (size_t)rr * DM + c) : unpack4(*(const u32x2*)xp);
;                         const f32x4 o = bs + gv[bj][n] * acc[ai][bj][m][n];
;                         u32x2 w; w.x = pk_bf16(o[0], o[1]); w.y = pk_bf16(o[2], o[3]);
;                         *(u32x2*)xp = w; } }
.LBB0_772:
	s_waitcnt vmcnt(3)
	v_pk_fma_f32 v[86:87], v[86:87], v[66:67], v[90:91]
	v_pk_fma_f32 v[84:85], v[84:85], v[64:65], v[88:89]
	s_and_b64 vcc, exec, s[4:5]
	v_cvt_pk_bf16_f32 v84, v84, v85
	v_cvt_pk_bf16_f32 v85, v86, v87
	global_store_dwordx2 v[92:93], v[84:85], off
	s_cbranch_vccnz .LBB0_774
	v_mov_b32_e32 v84, v232
	v_mov_b32_e32 v85, v233
	v_mov_b32_e32 v86, v234
	v_mov_b32_e32 v87, v235
	s_mov_b64 s[54:55], 0
	s_branch .LBB0_775

; __device__ __forceinline__ unsigned pk_bf16(float lo, float hi) { f32x2 v = {lo, hi}; bf16x2_t b = __builtin_convertvector(v, bf16x2_t); return __builtin_bit_cast(unsigned, b); }
; __device__ __forceinline__ f32x4 unpack4(u32x2 w) { return (f32x4){bf_lo(w.x), bf_hi(w.x), bf_lo(w.y), bf_hi(w.y)}; }
;     __device__ __forceinline__ void operator()(const f32x4 (&acc)[2][2][4][2], const Unit& u, int wr, int wc, int fr, int fq) const {
;     ...
;             for (int m = 0; m < 4; ++m) { const int rr = rowl + ai * HALF + m * 16;
; #pragma unroll
;                 for (int bj = 0; bj < 2; ++bj)
; #pragma unroll
;                     for (int n = 0; n < 2; ++n) { const int c = c0 + bj * HALF + n * 16; char* xp = (char*)xr + blk_off(rr, c, DM / 64);
;                         const f32x4 bs = base_f32 ? *(const f32x4*)(base_f32 + (size_t)rr * DM + c) : unpack4(*(const u32x2*)xp);
;                         const f32x4 o = bs + gv[bj][n] * acc[ai][bj][m][n];
;                         u32x2 w; w.x = pk_bf16(o[0], o[1]); w.y = pk_bf16(o[2], o[3]);
;                         *(u32x2*)xp = w; } }
.LBB0_777:
	s_waitcnt vmcnt(3)
	v_pk_fma_f32 v[82:83], v[82:83], v[58:59], v[86:87]
	v_pk_fma_f32 v[80:81], v[80:81], v[56:57], v[84:85]
	v_add_u32_e32 v84, 0x80, v166
	v_cvt_pk_bf16_f32 v80, v80, v81
	v_cvt_pk_bf16_f32 v81, v82, v83
	v_ashrrev_i32_e32 v85, 31, v84
	global_store_dwordx2 v[88:89], v[80:81], off
	v_lshlrev_b64 v[80:81], 13, v[84:85]
	v_lshl_add_u64 v[80:81], s[52:53], 0, v[80:81]
	s_and_b64 vcc, exec, s[4:5]
	v_lshl_add_u64 v[86:87], v[162:163], 2, v[80:81]
	s_cbranch_vccnz .LBB0_779
	global_load_dwordx4 v[202:205], v[86:87], off
	global_load_dwordx4 v[206:209], v[86:87], off offset:64
	global_load_dwordx4 v[218:221], v[86:87], off offset:512
	global_load_dwordx4 v[232:235], v[86:87], off offset:576
	s_waitcnt vmcnt(0)
	v_mov_b32_e32 v80, v202
	v_mov_b32_e32 v81, v203
	v_mov_b32_e32 v82, v204
	v_mov_b32_e32 v83, v205
	s_mov_b64 s[54:55], 0
	s_branch .LBB0_780

; __device__ __forceinline__ unsigned pk_bf16(float lo, float hi) { f32x2 v = {lo, hi}; bf16x2_t b = __builtin_convertvector(v, bf16x2_t); return __builtin_bit_cast(unsigned, b); }
; __device__ __forceinline__ f32x4 unpack4(u32x2 w) { return (f32x4){bf_lo(w.x), bf_hi(w.x), bf_lo(w.y), bf_hi(w.y)}; }
;     __device__ __forceinline__ void operator()(const f32x4 (&acc)[2][2][4][2], const Unit& u, int wr, int wc, int fr, int fq) const {
;     ...
;             for (int m = 0; m < 4; ++m) { const int rr = rowl + ai * HALF + m * 16;
; #pragma unroll
;                 for (int bj = 0; bj < 2; ++bj)
; #pragma unroll
;                     for (int n = 0; n < 2; ++n) { const int c = c0 + bj * HALF + n * 16; char* xp = (char*)xr + blk_off(rr, c, DM / 64);
;                         const f32x4 bs = base_f32 ? *(const f32x4*)(base_f32 + (size_t)rr * DM + c) : unpack4(*(const u32x2*)xp);
;                         const f32x4 o = bs + gv[bj][n] * acc[ai][bj][m][n];
;                         u32x2 w; w.x = pk_bf16(o[0], o[1]); w.y = pk_bf16(o[2], o[3]);
;                         *(u32x2*)xp = w; } }
.LBB0_782:
	s_waitcnt vmcnt(3)
	v_pk_fma_f32 v[70:71], v[70:71], v[78:79], v[82:83]
	v_pk_fma_f32 v[68:69], v[68:69], v[76:77], v[80:81]
	s_and_b64 vcc, exec, s[4:5]
	v_cvt_pk_bf16_f32 v68, v68, v69
	v_cvt_pk_bf16_f32 v69, v70, v71
	global_store_dwordx2 v[92:93], v[68:69], off
	s_cbranch_vccnz .LBB0_784
	v_mov_b32_e32 v68, v206
	v_mov_b32_e32 v69, v207
	v_mov_b32_e32 v70, v208
	v_mov_b32_e32 v71, v209
	s_mov_b64 s[54:55], 0
	s_branch .LBB0_785

; __device__ __forceinline__ unsigned pk_bf16(float lo, float hi) { f32x2 v = {lo, hi}; bf16x2_t b = __builtin_convertvector(v, bf16x2_t); return __builtin_bit_cast(unsigned, b); }
; __device__ __forceinline__ f32x4 unpack4(u32x2 w) { return (f32x4){bf_lo(w.x), bf_hi(w.x), bf_lo(w.y), bf_hi(w.y)}; }
;     __device__ __forceinline__ void operator()(const f32x4 (&acc)[2][2][4][2], const Unit& u, int wr, int wc, int fr, int fq) const {
;     ...
;             for (int m = 0; m < 4; ++m) { const int rr = rowl + ai * HALF + m * 16;
; #pragma unroll
;                 for (int bj = 0; bj < 2; ++bj)
; #pragma unroll
;                     for (int n = 0; n < 2; ++n) { const int c = c0 + bj * HALF + n * 16; char* xp = (char*)xr + blk_off(rr, c, DM / 64);
;                         const f32x4 bs = base_f32 ? *(const f32x4*)(base_f32 + (size_t)rr * DM + c) : unpack4(*(const u32x2*)xp);
;                         const f32x4 o = bs + gv[bj][n] * acc[ai][bj][m][n];
;                         u32x2 w; w.x = pk_bf16(o[0], o[1]); w.y = pk_bf16(o[2], o[3]);
;                         *(u32x2*)xp = w; } }
.LBB0_787:
	s_waitcnt vmcnt(3)
	v_pk_fma_f32 v[62:63], v[62:63], v[74:75], v[70:71]
	v_pk_fma_f32 v[60:61], v[60:61], v[72:73], v[68:69]
	s_and_b64 vcc, exec, s[4:5]
	v_cvt_pk_bf16_f32 v60, v60, v61
	v_cvt_pk_bf16_f32 v61, v62, v63
	global_store_dwordx2 v[80:81], v[60:61], off
	s_cbranch_vccnz .LBB0_789
	v_mov_b32_e32 v60, v218
	v_mov_b32_e32 v61, v219
	v_mov_b32_e32 v62, v220
	v_mov_b32_e32 v63, v221
	s_mov_b64 s[54:55], 0
	s_branch .LBB0_790

; __device__ __forceinline__ unsigned pk_bf16(float lo, float hi) { f32x2 v = {lo, hi}; bf16x2_t b = __builtin_convertvector(v, bf16x2_t); return __builtin_bit_cast(unsigned, b); }
; __device__ __forceinline__ f32x4 unpack4(u32x2 w) { return (f32x4){bf_lo(w.x), bf_hi(w.x), bf_lo(w.y), bf_hi(w.y)}; }
;     __device__ __forceinline__ void operator()(const f32x4 (&acc)[2][2][4][2], const Unit& u, int wr, int wc, int fr, int fq) const {
;     ...
;             for (int m = 0; m < 4; ++m) { const int rr = rowl + ai * HALF + m * 16;
; #pragma unroll
;                 for (int bj = 0; bj < 2; ++bj)
; #pragma unroll
;                     for (int n = 0; n < 2; ++n) { const int c = c0 + bj * HALF + n * 16; char* xp = (char*)xr + blk_off(rr, c, DM / 64);
;                         const f32x4 bs = base_f32 ? *(const f32x4*)(base_f32 + (size_t)rr * DM + c) : unpack4(*(const u32x2*)xp);
;                         const f32x4 o = bs + gv[bj][n] * acc[ai][bj][m][n];
;                         u32x2 w; w.x = pk_bf16(o[0], o[1]); w.y = pk_bf16(o[2], o[3]);
;                         *(u32x2*)xp = w; } }
.LBB0_792:
	s_waitcnt vmcnt(3)
	v_pk_fma_f32 v[54:55], v[54:55], v[66:67], v[62:63]
	v_pk_fma_f32 v[52:53], v[52:53], v[64:65], v[60:61]
	s_and_b64 vcc, exec, s[4:5]
	v_cvt_pk_bf16_f32 v52, v52, v53
	v_cvt_pk_bf16_f32 v53, v54, v55
	global_store_dwordx2 v[70:71], v[52:53], off
	s_cbranch_vccnz .LBB0_794
	v_mov_b32_e32 v52, v232
	v_mov_b32_e32 v53, v233
	v_mov_b32_e32 v54, v234
	v_mov_b32_e32 v55, v235
	s_mov_b64 s[54:55], 0
	s_branch .LBB0_795

; __device__ __forceinline__ unsigned pk_bf16(float lo, float hi) { f32x2 v = {lo, hi}; bf16x2_t b = __builtin_convertvector(v, bf16x2_t); return __builtin_bit_cast(unsigned, b); }
; __device__ __forceinline__ f32x4 unpack4(u32x2 w) { return (f32x4){bf_lo(w.x), bf_hi(w.x), bf_lo(w.y), bf_hi(w.y)}; }
;     __device__ __forceinline__ void operator()(const f32x4 (&acc)[2][2][4][2], const Unit& u, int wr, int wc, int fr, int fq) const {
;     ...
;             for (int m = 0; m < 4; ++m) { const int rr = rowl + ai * HALF + m * 16;
; #pragma unroll
;                 for (int bj = 0; bj < 2; ++bj)
; #pragma unroll
;                     for (int n = 0; n < 2; ++n) { const int c = c0 + bj * HALF + n * 16; char* xp = (char*)xr + blk_off(rr, c, DM / 64);
;                         const f32x4 bs = base_f32 ? *(const f32x4*)(base_f32 + (size_t)rr * DM + c) : unpack4(*(const u32x2*)xp);
;                         const f32x4 o = bs + gv[bj][n] * acc[ai][bj][m][n];
;                         u32x2 w; w.x = pk_bf16(o[0], o[1]); w.y = pk_bf16(o[2], o[3]);
;                         *(u32x2*)xp = w; } }
.LBB0_797:
	s_waitcnt vmcnt(3)
	v_pk_fma_f32 v[50:51], v[50:51], v[58:59], v[54:55]
	v_pk_fma_f32 v[48:49], v[48:49], v[56:57], v[52:53]
	s_and_b64 vcc, exec, s[4:5]
	v_cvt_pk_bf16_f32 v48, v48, v49
	v_cvt_pk_bf16_f32 v49, v50, v51
	global_store_dwordx2 v[62:63], v[48:49], off
	v_add_u32_e32 v62, 0x90, v166
	v_ashrrev_i32_e32 v63, 31, v62
	v_lshlrev_b64 v[48:49], 13, v[62:63]
	v_lshl_add_u64 v[48:49], s[52:53], 0, v[48:49]
	v_lshl_add_u64 v[52:53], v[162:163], 2, v[48:49]
	s_cbranch_vccnz .LBB0_799
	global_load_dwordx4 v[202:205], v[52:53], off
	global_load_dwordx4 v[206:209], v[52:53], off offset:64
	global_load_dwordx4 v[218:221], v[52:53], off offset:512
	global_load_dwordx4 v[232:235], v[52:53], off offset:576
	s_waitcnt vmcnt(0)
	v_mov_b32_e32 v48, v202
	v_mov_b32_e32 v49, v203
	v_mov_b32_e32 v50, v204
	v_mov_b32_e32 v51, v205
	s_mov_b64 s[54:55], 0
	s_branch .LBB0_800

; __device__ __forceinline__ unsigned pk_bf16(float lo, float hi) { f32x2 v = {lo, hi}; bf16x2_t b = __builtin_convertvector(v, bf16x2_t); return __builtin_bit_cast(unsigned, b); }
; __device__ __forceinline__ f32x4 unpack4(u32x2 w) { return (f32x4){bf_lo(w.x), bf_hi(w.x), bf_lo(w.y), bf_hi(w.y)}; }
;     __device__ __forceinline__ void operator()(const f32x4 (&acc)[2][2][4][2], const Unit& u, int wr, int wc, int fr, int fq) const {
;     ...
;             for (int m = 0; m < 4; ++m) { const int rr = rowl + ai * HALF + m * 16;
; #pragma unroll
;                 for (int bj = 0; bj < 2; ++bj)
; #pragma unroll
;                     for (int n = 0; n < 2; ++n) { const int c = c0 + bj * HALF + n * 16; char* xp = (char*)xr + blk_off(rr, c, DM / 64);
;                         const f32x4 bs = base_f32 ? *(const f32x4*)(base_f32 + (size_t)rr * DM + c) : unpack4(*(const u32x2*)xp);
;                         const f32x4 o = bs + gv[bj][n] * acc[ai][bj][m][n];
;                         u32x2 w; w.x = pk_bf16(o[0], o[1]); w.y = pk_bf16(o[2], o[3]);
;                         *(u32x2*)xp = w; } }
.LBB0_802:
	s_waitcnt vmcnt(3)
	v_pk_fma_f32 v[46:47], v[46:47], v[78:79], v[50:51]
	v_pk_fma_f32 v[44:45], v[44:45], v[76:77], v[48:49]
	s_and_b64 vcc, exec, s[4:5]
	v_cvt_pk_bf16_f32 v44, v44, v45
	v_cvt_pk_bf16_f32 v45, v46, v47
	global_store_dwordx2 v[70:71], v[44:45], off
	s_cbranch_vccnz .LBB0_804
	v_mov_b32_e32 v44, v206
	v_mov_b32_e32 v45, v207
	v_mov_b32_e32 v46, v208
	v_mov_b32_e32 v47, v209
	s_mov_b64 s[54:55], 0
	s_branch .LBB0_805

; __device__ __forceinline__ unsigned pk_bf16(float lo, float hi) { f32x2 v = {lo, hi}; bf16x2_t b = __builtin_convertvector(v, bf16x2_t); return __builtin_bit_cast(unsigned, b); }
; __device__ __forceinline__ f32x4 unpack4(u32x2 w) { return (f32x4){bf_lo(w.x), bf_hi(w.x), bf_lo(w.y), bf_hi(w.y)}; }
;     __device__ __forceinline__ void operator()(const f32x4 (&acc)[2][2][4][2], const Unit& u, int wr, int wc, int fr, int fq) const {
;     ...
;             for (int m = 0; m < 4; ++m) { const int rr = rowl + ai * HALF + m * 16;
; #pragma unroll
;                 for (int bj = 0; bj < 2; ++bj)
; #pragma unroll
;                     for (int n = 0; n < 2; ++n) { const int c = c0 + bj * HALF + n * 16; char* xp = (char*)xr + blk_off(rr, c, DM / 64);
;                         const f32x4 bs = base_f32 ? *(const f32x4*)(base_f32 + (size_t)rr * DM + c) : unpack4(*(const u32x2*)xp);
;                         const f32x4 o = bs + gv[bj][n] * acc[ai][bj][m][n];
;                         u32x2 w; w.x = pk_bf16(o[0], o[1]); w.y = pk_bf16(o[2], o[3]);
;                         *(u32x2*)xp = w; } }
.LBB0_807:
	s_waitcnt vmcnt(3)
	v_pk_fma_f32 v[42:43], v[42:43], v[74:75], v[46:47]
	v_pk_fma_f32 v[40:41], v[40:41], v[72:73], v[44:45]
	s_and_b64 vcc, exec, s[4:5]
	v_cvt_pk_bf16_f32 v40, v40, v41
	v_cvt_pk_bf16_f32 v41, v42, v43
	global_store_dwordx2 v[48:49], v[40:41], off
	s_cbranch_vccnz .LBB0_809
	v_mov_b32_e32 v40, v218
	v_mov_b32_e32 v41, v219
	v_mov_b32_e32 v42, v220
	v_mov_b32_e32 v43, v221
	s_mov_b64 s[54:55], 0
	s_branch .LBB0_810

; __device__ __forceinline__ unsigned pk_bf16(float lo, float hi) { f32x2 v = {lo, hi}; bf16x2_t b = __builtin_convertvector(v, bf16x2_t); return __builtin_bit_cast(unsigned, b); }
; __device__ __forceinline__ f32x4 unpack4(u32x2 w) { return (f32x4){bf_lo(w.x), bf_hi(w.x), bf_lo(w.y), bf_hi(w.y)}; }
;     __device__ __forceinline__ void operator()(const f32x4 (&acc)[2][2][4][2], const Unit& u, int wr, int wc, int fr, int fq) const {
;     ...
;             for (int m = 0; m < 4; ++m) { const int rr = rowl + ai * HALF + m * 16;
; #pragma unroll
;                 for (int bj = 0; bj < 2; ++bj)
; #pragma unroll
;                     for (int n = 0; n < 2; ++n) { const int c = c0 + bj * HALF + n * 16; char* xp = (char*)xr + blk_off(rr, c, DM / 64);
;                         const f32x4 bs = base_f32 ? *(const f32x4*)(base_f32 + (size_t)rr * DM + c) : unpack4(*(const u32x2*)xp);
;                         const f32x4 o = bs + gv[bj][n] * acc[ai][bj][m][n];
;                         u32x2 w; w.x = pk_bf16(o[0], o[1]); w.y = pk_bf16(o[2], o[3]);
;                         *(u32x2*)xp = w; } }
.LBB0_812:
	s_waitcnt vmcnt(3)
	v_pk_fma_f32 v[38:39], v[38:39], v[66:67], v[42:43]
	v_pk_fma_f32 v[36:37], v[36:37], v[64:65], v[40:41]
	s_and_b64 vcc, exec, s[4:5]
	v_cvt_pk_bf16_f32 v36, v36, v37
	v_cvt_pk_bf16_f32 v37, v38, v39
	global_store_dwordx2 v[44:45], v[36:37], off
	s_cbranch_vccnz .LBB0_814
	v_mov_b32_e32 v36, v232
	v_mov_b32_e32 v37, v233
	v_mov_b32_e32 v38, v234
	v_mov_b32_e32 v39, v235
	s_mov_b64 s[54:55], 0
	s_branch .LBB0_815

; __device__ __forceinline__ unsigned pk_bf16(float lo, float hi) { f32x2 v = {lo, hi}; bf16x2_t b = __builtin_convertvector(v, bf16x2_t); return __builtin_bit_cast(unsigned, b); }
; __device__ __forceinline__ f32x4 unpack4(u32x2 w) { return (f32x4){bf_lo(w.x), bf_hi(w.x), bf_lo(w.y), bf_hi(w.y)}; }
;     __device__ __forceinline__ void operator()(const f32x4 (&acc)[2][2][4][2], const Unit& u, int wr, int wc, int fr, int fq) const {
;     ...
;             for (int m = 0; m < 4; ++m) { const int rr = rowl + ai * HALF + m * 16;
; #pragma unroll
;                 for (int bj = 0; bj < 2; ++bj)
; #pragma unroll
;                     for (int n = 0; n < 2; ++n) { const int c = c0 + bj * HALF + n * 16; char* xp = (char*)xr + blk_off(rr, c, DM / 64);
;                         const f32x4 bs = base_f32 ? *(const f32x4*)(base_f32 + (size_t)rr * DM + c) : unpack4(*(const u32x2*)xp);
;                         const f32x4 o = bs + gv[bj][n] * acc[ai][bj][m][n];
;                         u32x2 w; w.x = pk_bf16(o[0], o[1]); w.y = pk_bf16(o[2], o[3]);
;                         *(u32x2*)xp = w; } }
.LBB0_817:
	s_waitcnt vmcnt(3)
	v_pk_fma_f32 v[34:35], v[34:35], v[58:59], v[38:39]
	v_pk_fma_f32 v[32:33], v[32:33], v[56:57], v[36:37]
	s_and_b64 vcc, exec, s[4:5]
	v_cvt_pk_bf16_f32 v32, v32, v33
	v_cvt_pk_bf16_f32 v33, v34, v35
	global_store_dwordx2 v[40:41], v[32:33], off
	v_add_u32_e32 v40, 0xa0, v166
	v_ashrrev_i32_e32 v41, 31, v40
	v_lshlrev_b64 v[32:33], 13, v[40:41]
	v_lshl_add_u64 v[32:33], s[52:53], 0, v[32:33]
	v_lshl_add_u64 v[36:37], v[162:163], 2, v[32:33]
	s_cbranch_vccnz .LBB0_819
	global_load_dwordx4 v[202:205], v[36:37], off
	global_load_dwordx4 v[206:209], v[36:37], off offset:64
	global_load_dwordx4 v[218:221], v[36:37], off offset:512
	global_load_dwordx4 v[232:235], v[36:37], off offset:576
	s_waitcnt vmcnt(0)
	v_mov_b32_e32 v32, v202
	v_mov_b32_e32 v33, v203
	v_mov_b32_e32 v34, v204
	v_mov_b32_e32 v35, v205
	s_mov_b64 s[54:55], 0
	s_branch .LBB0_820

; __device__ __forceinline__ unsigned pk_bf16(float lo, float hi) { f32x2 v = {lo, hi}; bf16x2_t b = __builtin_convertvector(v, bf16x2_t); return __builtin_bit_cast(unsigned, b); }
; __device__ __forceinline__ f32x4 unpack4(u32x2 w) { return (f32x4){bf_lo(w.x), bf_hi(w.x), bf_lo(w.y), bf_hi(w.y)}; }
;     __device__ __forceinline__ void operator()(const f32x4 (&acc)[2][2][4][2], const Unit& u, int wr, int wc, int fr, int fq) const {
;     ...
;             for (int m = 0; m < 4; ++m) { const int rr = rowl + ai * HALF + m * 16;
; #pragma unroll
;                 for (int bj = 0; bj < 2; ++bj)
; #pragma unroll
;                     for (int n = 0; n < 2; ++n) { const int c = c0 + bj * HALF + n * 16; char* xp = (char*)xr + blk_off(rr, c, DM / 64);
;                         const f32x4 bs = base_f32 ? *(const f32x4*)(base_f32 + (size_t)rr * DM + c) : unpack4(*(const u32x2*)xp);
;                         const f32x4 o = bs + gv[bj][n] * acc[ai][bj][m][n];
;                         u32x2 w; w.x = pk_bf16(o[0], o[1]); w.y = pk_bf16(o[2], o[3]);
;                         *(u32x2*)xp = w; } }
.LBB0_822:
	s_waitcnt vmcnt(3)
	v_pk_fma_f32 v[30:31], v[30:31], v[78:79], v[34:35]
	v_pk_fma_f32 v[28:29], v[28:29], v[76:77], v[32:33]
	s_and_b64 vcc, exec, s[4:5]
	v_cvt_pk_bf16_f32 v28, v28, v29
	v_cvt_pk_bf16_f32 v29, v30, v31
	global_store_dwordx2 v[42:43], v[28:29], off
	s_cbranch_vccnz .LBB0_824
	v_mov_b32_e32 v28, v206
	v_mov_b32_e32 v29, v207
	v_mov_b32_e32 v30, v208
	v_mov_b32_e32 v31, v209
	s_mov_b64 s[54:55], 0
	s_branch .LBB0_825

; __device__ __forceinline__ unsigned pk_bf16(float lo, float hi) { f32x2 v = {lo, hi}; bf16x2_t b = __builtin_convertvector(v, bf16x2_t); return __builtin_bit_cast(unsigned, b); }
; __device__ __forceinline__ f32x4 unpack4(u32x2 w) { return (f32x4){bf_lo(w.x), bf_hi(w.x), bf_lo(w.y), bf_hi(w.y)}; }
;     __device__ __forceinline__ void operator()(const f32x4 (&acc)[2][2][4][2], const Unit& u, int wr, int wc, int fr, int fq) const {
;     ...
;             for (int m = 0; m < 4; ++m) { const int rr = rowl + ai * HALF + m * 16;
; #pragma unroll
;                 for (int bj = 0; bj < 2; ++bj)
; #pragma unroll
;                     for (int n = 0; n < 2; ++n) { const int c = c0 + bj * HALF + n * 16; char* xp = (char*)xr + blk_off(rr, c, DM / 64);
;                         const f32x4 bs = base_f32 ? *(const f32x4*)(base_f32 + (size_t)rr * DM + c) : unpack4(*(const u32x2*)xp);
;                         const f32x4 o = bs + gv[bj][n] * acc[ai][bj][m][n];
;                         u32x2 w; w.x = pk_bf16(o[0], o[1]); w.y = pk_bf16(o[2], o[3]);
;                         *(u32x2*)xp = w; } }
.LBB0_827:
	s_waitcnt vmcnt(3)
	v_pk_fma_f32 v[26:27], v[26:27], v[74:75], v[30:31]
	v_pk_fma_f32 v[24:25], v[24:25], v[72:73], v[28:29]
	s_and_b64 vcc, exec, s[4:5]
	v_cvt_pk_bf16_f32 v24, v24, v25
	v_cvt_pk_bf16_f32 v25, v26, v27
	global_store_dwordx2 v[32:33], v[24:25], off
	s_cbranch_vccnz .LBB0_829
	v_mov_b32_e32 v24, v218
	v_mov_b32_e32 v25, v219
	v_mov_b32_e32 v26, v220
	v_mov_b32_e32 v27, v221
	s_mov_b64 s[54:55], 0
	s_branch .LBB0_830

; __device__ __forceinline__ unsigned pk_bf16(float lo, float hi) { f32x2 v = {lo, hi}; bf16x2_t b = __builtin_convertvector(v, bf16x2_t); return __builtin_bit_cast(unsigned, b); }
; __device__ __forceinline__ f32x4 unpack4(u32x2 w) { return (f32x4){bf_lo(w.x), bf_hi(w.x), bf_lo(w.y), bf_hi(w.y)}; }
;     __device__ __forceinline__ void operator()(const f32x4 (&acc)[2][2][4][2], const Unit& u, int wr, int wc, int fr, int fq) const {
;     ...
;             for (int m = 0; m < 4; ++m) { const int rr = rowl + ai * HALF + m * 16;
; #pragma unroll
;                 for (int bj = 0; bj < 2; ++bj)
; #pragma unroll
;                     for (int n = 0; n < 2; ++n) { const int c = c0 + bj * HALF + n * 16; char* xp = (char*)xr + blk_off(rr, c, DM / 64);
;                         const f32x4 bs = base_f32 ? *(const f32x4*)(base_f32 + (size_t)rr * DM + c) : unpack4(*(const u32x2*)xp);
;                         const f32x4 o = bs + gv[bj][n] * acc[ai][bj][m][n];
;                         u32x2 w; w.x = pk_bf16(o[0], o[1]); w.y = pk_bf16(o[2], o[3]);
;                         *(u32x2*)xp = w; } }
.LBB0_832:
	s_waitcnt vmcnt(3)
	v_pk_fma_f32 v[22:23], v[22:23], v[66:67], v[26:27]
	v_pk_fma_f32 v[20:21], v[20:21], v[64:65], v[24:25]
	s_and_b64 vcc, exec, s[4:5]
	v_cvt_pk_bf16_f32 v20, v20, v21
	v_cvt_pk_bf16_f32 v21, v22, v23
	global_store_dwordx2 v[28:29], v[20:21], off
	s_cbranch_vccnz .LBB0_834
	v_mov_b32_e32 v20, v232
	v_mov_b32_e32 v21, v233
	v_mov_b32_e32 v22, v234
	v_mov_b32_e32 v23, v235
	s_mov_b64 s[54:55], 0
	s_branch .LBB0_835

; __device__ __forceinline__ unsigned pk_bf16(float lo, float hi) { f32x2 v = {lo, hi}; bf16x2_t b = __builtin_convertvector(v, bf16x2_t); return __builtin_bit_cast(unsigned, b); }
; __device__ __forceinline__ f32x4 unpack4(u32x2 w) { return (f32x4){bf_lo(w.x), bf_hi(w.x), bf_lo(w.y), bf_hi(w.y)}; }
;     __device__ __forceinline__ void operator()(const f32x4 (&acc)[2][2][4][2], const Unit& u, int wr, int wc, int fr, int fq) const {
;     ...
;             for (int m = 0; m < 4; ++m) { const int rr = rowl + ai * HALF + m * 16;
; #pragma unroll
;                 for (int bj = 0; bj < 2; ++bj)
; #pragma unroll
;                     for (int n = 0; n < 2; ++n) { const int c = c0 + bj * HALF + n * 16; char* xp = (char*)xr + blk_off(rr, c, DM / 64);
;                         const f32x4 bs = base_f32 ? *(const f32x4*)(base_f32 + (size_t)rr * DM + c) : unpack4(*(const u32x2*)xp);
;                         const f32x4 o = bs + gv[bj][n] * acc[ai][bj][m][n];
;                         u32x2 w; w.x = pk_bf16(o[0], o[1]); w.y = pk_bf16(o[2], o[3]);
;                         *(u32x2*)xp = w; } }
.LBB0_837:
	s_waitcnt vmcnt(3)
	v_pk_fma_f32 v[18:19], v[18:19], v[58:59], v[22:23]
	v_pk_fma_f32 v[16:17], v[16:17], v[56:57], v[20:21]
	s_and_b64 vcc, exec, s[4:5]
	v_cvt_pk_bf16_f32 v16, v16, v17
	v_cvt_pk_bf16_f32 v17, v18, v19
	global_store_dwordx2 v[24:25], v[16:17], off
	v_add_u32_e32 v24, 0xb0, v166
	v_ashrrev_i32_e32 v25, 31, v24
	v_lshlrev_b64 v[16:17], 13, v[24:25]
	v_lshl_add_u64 v[16:17], s[52:53], 0, v[16:17]
	v_lshl_add_u64 v[20:21], v[162:163], 2, v[16:17]
	s_cbranch_vccnz .LBB0_839
	global_load_dwordx4 v[202:205], v[20:21], off
	global_load_dwordx4 v[206:209], v[20:21], off offset:64
	global_load_dwordx4 v[218:221], v[20:21], off offset:512
	global_load_dwordx4 v[232:235], v[20:21], off offset:576
	s_waitcnt vmcnt(0)
	v_mov_b32_e32 v16, v202
	v_mov_b32_e32 v17, v203
	v_mov_b32_e32 v18, v204
	v_mov_b32_e32 v19, v205
	s_mov_b64 s[54:55], 0
	s_branch .LBB0_840

; __device__ __forceinline__ unsigned pk_bf16(float lo, float hi) { f32x2 v = {lo, hi}; bf16x2_t b = __builtin_convertvector(v, bf16x2_t); return __builtin_bit_cast(unsigned, b); }
; __device__ __forceinline__ f32x4 unpack4(u32x2 w) { return (f32x4){bf_lo(w.x), bf_hi(w.x), bf_lo(w.y), bf_hi(w.y)}; }
;     __device__ __forceinline__ void operator()(const f32x4 (&acc)[2][2][4][2], const Unit& u, int wr, int wc, int fr, int fq) const {
;     ...
;             for (int m = 0; m < 4; ++m) { const int rr = rowl + ai * HALF + m * 16;
; #pragma unroll
;                 for (int bj = 0; bj < 2; ++bj)
; #pragma unroll
;                     for (int n = 0; n < 2; ++n) { const int c = c0 + bj * HALF + n * 16; char* xp = (char*)xr + blk_off(rr, c, DM / 64);
;                         const f32x4 bs = base_f32 ? *(const f32x4*)(base_f32 + (size_t)rr * DM + c) : unpack4(*(const u32x2*)xp);
;                         const f32x4 o = bs + gv[bj][n] * acc[ai][bj][m][n];
;                         u32x2 w; w.x = pk_bf16(o[0], o[1]); w.y = pk_bf16(o[2], o[3]);
;                         *(u32x2*)xp = w; } }
.LBB0_842:
	s_waitcnt vmcnt(3)
	v_pk_fma_f32 v[14:15], v[14:15], v[78:79], v[18:19]
	v_pk_fma_f32 v[12:13], v[12:13], v[76:77], v[16:17]
	s_and_b64 vcc, exec, s[4:5]
	v_cvt_pk_bf16_f32 v12, v12, v13
	v_cvt_pk_bf16_f32 v13, v14, v15
	global_store_dwordx2 v[26:27], v[12:13], off
	s_cbranch_vccnz .LBB0_844
	v_mov_b32_e32 v12, v206
	v_mov_b32_e32 v13, v207
	v_mov_b32_e32 v14, v208
	v_mov_b32_e32 v15, v209
	s_mov_b64 s[54:55], 0
	s_branch .LBB0_845

; __device__ __forceinline__ unsigned pk_bf16(float lo, float hi) { f32x2 v = {lo, hi}; bf16x2_t b = __builtin_convertvector(v, bf16x2_t); return __builtin_bit_cast(unsigned, b); }
; __device__ __forceinline__ f32x4 unpack4(u32x2 w) { return (f32x4){bf_lo(w.x), bf_hi(w.x), bf_lo(w.y), bf_hi(w.y)}; }
;     __device__ __forceinline__ void operator()(const f32x4 (&acc)[2][2][4][2], const Unit& u, int wr, int wc, int fr, int fq) const {
;     ...
;             for (int m = 0; m < 4; ++m) { const int rr = rowl + ai * HALF + m * 16;
; #pragma unroll
;                 for (int bj = 0; bj < 2; ++bj)
; #pragma unroll
;                     for (int n = 0; n < 2; ++n) { const int c = c0 + bj * HALF + n * 16; char* xp = (char*)xr + blk_off(rr, c, DM / 64);
;                         const f32x4 bs = base_f32 ? *(const f32x4*)(base_f32 + (size_t)rr * DM + c) : unpack4(*(const u32x2*)xp);
;                         const f32x4 o = bs + gv[bj][n] * acc[ai][bj][m][n];
;                         u32x2 w; w.x = pk_bf16(o[0], o[1]); w.y = pk_bf16(o[2], o[3]);
;                         *(u32x2*)xp = w; } }
.LBB0_847:
	s_waitcnt vmcnt(3)
	v_pk_fma_f32 v[10:11], v[10:11], v[74:75], v[14:15]
	v_pk_fma_f32 v[8:9], v[8:9], v[72:73], v[12:13]
	s_and_b64 vcc, exec, s[4:5]
	v_cvt_pk_bf16_f32 v8, v8, v9
	v_cvt_pk_bf16_f32 v9, v10, v11
	global_store_dwordx2 v[16:17], v[8:9], off
	s_cbranch_vccnz .LBB0_849
	v_mov_b32_e32 v8, v218
	v_mov_b32_e32 v9, v219
	v_mov_b32_e32 v10, v220
	v_mov_b32_e32 v11, v221
	s_mov_b64 s[54:55], 0
	s_branch .LBB0_850

; __device__ __forceinline__ unsigned pk_bf16(float lo, float hi) { f32x2 v = {lo, hi}; bf16x2_t b = __builtin_convertvector(v, bf16x2_t); return __builtin_bit_cast(unsigned, b); }
; __device__ __forceinline__ f32x4 unpack4(u32x2 w) { return (f32x4){bf_lo(w.x), bf_hi(w.x), bf_lo(w.y), bf_hi(w.y)}; }
;     __device__ __forceinline__ void operator()(const f32x4 (&acc)[2][2][4][2], const Unit& u, int wr, int wc, int fr, int fq) const {
;     ...
;             for (int m = 0; m < 4; ++m) { const int rr = rowl + ai * HALF + m * 16;
; #pragma unroll
;                 for (int bj = 0; bj < 2; ++bj)
; #pragma unroll
;                     for (int n = 0; n < 2; ++n) { const int c = c0 + bj * HALF + n * 16; char* xp = (char*)xr + blk_off(rr, c, DM / 64);
;                         const f32x4 bs = base_f32 ? *(const f32x4*)(base_f32 + (size_t)rr * DM + c) : unpack4(*(const u32x2*)xp);
;                         const f32x4 o = bs + gv[bj][n] * acc[ai][bj][m][n];
;                         u32x2 w; w.x = pk_bf16(o[0], o[1]); w.y = pk_bf16(o[2], o[3]);
;                         *(u32x2*)xp = w; } }
.LBB0_852:
	s_waitcnt vmcnt(3)
	v_pk_fma_f32 v[6:7], v[6:7], v[66:67], v[10:11]
	v_pk_fma_f32 v[4:5], v[4:5], v[64:65], v[8:9]
	s_and_b64 vcc, exec, s[4:5]
	v_cvt_pk_bf16_f32 v4, v4, v5
	v_cvt_pk_bf16_f32 v5, v6, v7
	global_store_dwordx2 v[12:13], v[4:5], off
	s_cbranch_vccnz .LBB0_854
	v_mov_b32_e32 v4, v232
	v_mov_b32_e32 v5, v233
	v_mov_b32_e32 v6, v234
	v_mov_b32_e32 v7, v235
	s_mov_b64 s[4:5], 0
	s_branch .LBB0_855

; __device__ __forceinline__ unsigned pk_bf16(float lo, float hi) { f32x2 v = {lo, hi}; bf16x2_t b = __builtin_convertvector(v, bf16x2_t); return __builtin_bit_cast(unsigned, b); }
; __device__ __forceinline__ f32x4 unpack4(u32x2 w) { return (f32x4){bf_lo(w.x), bf_hi(w.x), bf_lo(w.y), bf_hi(w.y)}; }
;     __device__ __forceinline__ void operator()(const f32x4 (&acc)[2][2][4][2], const Unit& u, int wr, int wc, int fr, int fq) const {
;     ...
;             for (int m = 0; m < 4; ++m) { const int rr = rowl + ai * HALF + m * 16;
; #pragma unroll
;                 for (int bj = 0; bj < 2; ++bj)
; #pragma unroll
;                     for (int n = 0; n < 2; ++n) { const int c = c0 + bj * HALF + n * 16; char* xp = (char*)xr + blk_off(rr, c, DM / 64);
;                         const f32x4 bs = base_f32 ? *(const f32x4*)(base_f32 + (size_t)rr * DM + c) : unpack4(*(const u32x2*)xp);
;                         const f32x4 o = bs + gv[bj][n] * acc[ai][bj][m][n];
;                         u32x2 w; w.x = pk_bf16(o[0], o[1]); w.y = pk_bf16(o[2], o[3]);
;                         *(u32x2*)xp = w; } }
.LBB0_857:
	s_waitcnt vmcnt(3)
	v_pk_fma_f32 v[2:3], v[2:3], v[58:59], v[6:7]
	v_pk_fma_f32 v[0:1], v[0:1], v[56:57], v[4:5]
	s_andn2_b64 vcc, exec, s[2:3]
	v_cvt_pk_bf16_f32 v0, v0, v1
	v_cvt_pk_bf16_f32 v1, v2, v3
	s_mov_b64 s[2:3], -1
	global_store_dwordx2 v[8:9], v[0:1], off
	s_cbranch_vccnz .LBB0_686
	s_andn2_b64 vcc, exec, s[14:15]
	s_cbranch_vccnz .LBB0_685
	s_barrier
	s_branch .LBB0_685
